# c_phase preheader: with Q prefetched wait only vmcnt(4) so the epilogue stores stay in flight
# baseline (speedup 1.0000x reference)
; #define GAS __attribute__((address_space(1)))
; __device__ __forceinline__ void c_phase(const bf16_t* Z, bf16_t* MIX, float* LSE, ldsp lds, int pi, int bx, int G, unsigned& gt, int wave0, int ucount) {
;     ...
;     for (; u < uend; ++u) {
;         C_DEC(u, b, hp, rs, blk);
;         const int head = 2 * hp + hsel, q0 = 128 * blk + 32 * gq, ql = q0 + r32;
;         const int kt0 = blk >= 1 ? 2 * blk - 2 : 0, kt1 = 2 * blk + 1;
;         const bf16_t* kvp = C_KVP(b, hp, rs);
;         const bool has_next = u + 1 < uend;
;         const int un = has_next ? u + 1 : u;
;         C_DEC(un, bn, hpn, rsn, blkn);
;         const int kt0n = blkn >= 1 ? 2 * blkn - 2 : 0;
;         const bf16_t* kvpn = C_KVP(bn, hpn, rsn) + kt0n * tstride;
;         bf16x8 qr[4]; q_load(qr, C_QROW(b, hp, rs, blk), hi);
;         GAS float* lsep = (GAS float*)(LSE + ((size_t)b * T + (size_t)q0 * dil + rs) * 16 + head + llane);
;         bf16_t* orow = MIX + ((size_t)b * T + (size_t)q0 * dil + rs) * 1024 + head * 64 + olane;
;         const size_t ostep = (size_t)8 * dil * 1024;
;         u32x4 orun[4] = {z4, z4, z4, z4}; float lse_old = 0.f;
;         float m = 0.f, l = 0.f; bool started = false;
;         f32x16 o[2], negm; splat16(negm, 0.f);
;         splat16(o[0], 0.f); splat16(o[1], 0.f);
;         for (int kt = kt0; kt <= kt1; ++kt) {
.LBB0_1034:
	s_ashr_i32 s0, s1, s33
	v_readlane_b32 s36, v254, 18
	s_and_b32 s36, s0, s35
	s_lshr_b32 s0, s1, 4
	s_and_b32 s9, s1, s34
	s_and_b32 s0, s0, 14
	v_readlane_b32 s8, v254, 16
	s_add_i32 s14, s0, s8
	s_lshl_b32 s10, s9, 7
	v_readlane_b32 s8, v254, 41
	s_lshl_b32 s87, s9, 1
	s_ashr_i32 s12, s1, 8
	s_add_i32 s8, s10, s8
	s_add_i32 s11, s87, -2
	s_cmp_lg_u32 s9, 0
	s_cselect_b32 s84, s11, 0
	s_or_b32 s78, s87, 1
	s_add_i32 s86, s1, 1
	v_readlane_b32 s40, v254, 22
	v_readlane_b32 s41, v254, 23
	s_cmp_lt_i32 s86, s65
	s_mul_i32 s11, s12, 48
	s_cselect_b64 s[40:41], -1, 0
	s_cmp_ge_i32 s86, s65
	s_cselect_b64 s[92:93], -1, 0
	s_add_i32 s16, s14, s11
	s_ashr_i32 s9, s8, 31
	v_readlane_b32 s13, v254, 40
	s_ashr_i32 s17, s16, 31
	s_lshl_b64 s[18:19], s[8:9], s13
	s_add_u32 s18, s18, s36
	s_addc_u32 s19, s19, 0
	s_lshl_b64 s[16:17], s[16:17], 19
	s_lshl_b64 s[20:21], s[18:19], 7
	s_cmp_eq_u32 s101, 1
	s_cbranch_scc1 .Lc_qskip
	v_lshl_add_u64 v[16:17], v[188:189], 0, s[16:17]
	v_lshl_add_u64 v[16:17], v[16:17], 0, s[20:21]
	global_load_dwordx4 v[160:163], v[16:17], off
	global_load_dwordx4 v[164:167], v[16:17], off offset:32
	global_load_dwordx4 v[168:171], v[16:17], off offset:64
	global_load_dwordx4 v[172:175], v[16:17], off offset:96
.Lc_qskip:
	s_ashr_i32 s13, s12, 31
	s_lshl_b64 s[12:13], s[12:13], 12
	s_add_u32 s12, s18, s12
	s_addc_u32 s13, s19, s13
	s_lshl_b64 s[16:17], s[12:13], 6
	s_add_u32 s9, s4, s16
	s_addc_u32 s18, s29, s17
	s_ashr_i32 s15, s14, 31
	s_lshl_b64 s[16:17], s[14:15], 2
	s_add_u32 s16, s9, s16
	s_addc_u32 s17, s18, s17
	s_lshl_b64 s[12:13], s[12:13], 11
	v_readlane_b32 s9, v255, 18
	s_add_u32 s9, s9, s12
	v_readlane_b32 s12, v255, 19
	s_addc_u32 s15, s12, s13
	s_lshl_b32 s12, s14, 6
	s_ashr_i32 s13, s12, 31
	s_lshl_b64 s[12:13], s[12:13], 1
	s_add_u32 s12, s9, s12
	s_addc_u32 s13, s15, s13
	s_waitcnt vmcnt(12)
	v_mov_b32_e32 v191, v177
	v_mov_b64_e32 v[62:63], v[14:15]
	v_mov_b64_e32 v[46:47], v[14:15]
	v_mov_b64_e32 v[30:31], v[14:15]
	v_readlane_b32 s37, v254, 19
	v_lshl_add_u64 v[194:195], v[182:183], 2, s[16:17]
	v_lshl_add_u64 v[192:193], s[12:13], 0, v[190:191]
	v_mov_b64_e32 v[60:61], v[12:13]
	v_mov_b64_e32 v[58:59], v[10:11]
	v_mov_b64_e32 v[56:57], v[8:9]
	v_mov_b64_e32 v[54:55], v[6:7]
	v_mov_b64_e32 v[52:53], v[4:5]
	v_mov_b64_e32 v[50:51], v[2:3]
	v_mov_b64_e32 v[48:49], v[0:1]
	v_mov_b64_e32 v[44:45], v[12:13]
	v_mov_b64_e32 v[42:43], v[10:11]
	v_mov_b64_e32 v[40:41], v[8:9]
	v_mov_b64_e32 v[38:39], v[6:7]
	v_mov_b64_e32 v[36:37], v[4:5]
	v_mov_b64_e32 v[34:35], v[2:3]
	v_mov_b64_e32 v[32:33], v[0:1]
	v_mov_b64_e32 v[28:29], v[12:13]
	v_mov_b64_e32 v[26:27], v[10:11]
	v_mov_b64_e32 v[24:25], v[8:9]
	v_mov_b64_e32 v[22:23], v[6:7]
	v_mov_b64_e32 v[20:21], v[4:5]
	v_mov_b64_e32 v[18:19], v[2:3]
	v_mov_b64_e32 v[16:17], v[0:1]
	s_ashr_i32 s98, s86, 8
	s_mul_i32 s98, s98, 48
	s_lshr_b32 s99, s86, 4
	s_and_b32 s99, s99, 14
	s_add_i32 s98, s98, s99
	v_readlane_b32 s99, v254, 16
	s_nop 0
	s_add_i32 s98, s98, s99
	s_lshl_b32 s98, s98, 12
	s_and_b32 s99, s86, s34
	s_lshl_b32 s99, s99, 7
	v_readlane_b32 s100, v254, 41
	s_nop 0
	s_add_i32 s99, s99, s100
	v_readlane_b32 s100, v254, 40
	s_nop 0
	s_lshl_b32 s99, s99, s100
	s_ashr_i32 s100, s86, s33
	s_and_b32 s100, s100, s35
	s_add_i32 s99, s99, s100
	s_add_i32 s98, s98, s99
	s_lshl_b32 s98, s98, 7
	s_cmp_gt_i32 s84, s78
	v_readlane_b32 s38, v254, 20
	v_readlane_b32 s39, v254, 21
	v_readlane_b32 s42, v254, 24
	v_readlane_b32 s43, v254, 25
	v_readlane_b32 s44, v254, 26
	v_readlane_b32 s45, v254, 27
	v_readlane_b32 s46, v254, 28
	v_readlane_b32 s47, v254, 29
	v_readlane_b32 s48, v254, 30
	v_readlane_b32 s49, v254, 31
	v_readlane_b32 s50, v254, 32
	v_readlane_b32 s51, v254, 33
	s_cbranch_scc1 .LBB0_1074
	s_add_i32 s0, s11, s0
	s_add_i32 s12, s0, 16
	s_ashr_i32 s13, s12, 31
	s_lshl_b64 s[12:13], s[12:13], 19
	s_add_u32 s0, s80, s12
	s_addc_u32 s9, s81, s13
	s_lshl_b64 s[12:13], s[36:37], 7
	s_add_u32 s85, s0, s12
	s_addc_u32 s0, s9, s13
	s_and_b64 s[12:13], s[40:41], exec
	s_cselect_b32 s1, s86, s1
	s_ashr_i32 s9, s1, 8
	s_lshr_b32 s11, s1, 4
	s_mul_i32 s9, s9, 48
	s_and_b32 s11, s11, 14
	s_or_b32 s9, s9, s11
	s_add_i32 s12, s9, 16
	s_ashr_i32 s13, s12, 31
	s_lshl_b64 s[12:13], s[12:13], 19
	s_add_u32 s9, s80, s12
	s_addc_u32 s11, s81, s13
	s_ashr_i32 s12, s1, s33
	s_and_b32 s12, s12, s35
	s_lshl_b32 s12, s12, 7
	s_add_u32 s9, s9, s12
	s_addc_u32 s11, s11, 0
	s_and_b32 s1, s1, s34
	s_lshl_b32 s12, s1, 1
	s_add_i32 s12, s12, -2
	s_mov_b32 s4, s65
	s_cmp_lg_u32 s1, 0
	s_mov_b32 s1, s37
	s_cselect_b32 s36, s12, 0
	v_writelane_b32 v254, s0, 18
	s_waitcnt vmcnt(8)
	v_mov_b32_e32 v144, 0
	s_mov_b32 s95, s34
	v_writelane_b32 v254, s1, 19
	v_writelane_b32 v254, s2, 20
	v_writelane_b32 v254, s3, 21
	v_writelane_b32 v254, s4, 22
	v_writelane_b32 v254, s5, 23
	v_writelane_b32 v254, s6, 24
	v_writelane_b32 v254, s7, 25
	v_writelane_b32 v254, s8, 26
	v_writelane_b32 v254, s9, 27
	v_writelane_b32 v254, s10, 28
	v_writelane_b32 v254, s11, 29
	v_writelane_b32 v254, s12, 30
	v_writelane_b32 v254, s13, 31
	v_writelane_b32 v254, s14, 32
	v_writelane_b32 v254, s15, 33
	s_lshl_b64 s[12:13], s[36:37], s72
	s_lshl_b64 s[12:13], s[12:13], 1
	s_add_u32 s1, s9, s12
	s_addc_u32 s74, s11, s13
	s_or_b32 s75, s8, 31
	s_add_i32 s76, s8, 0xffffff80
	v_readlane_b32 s8, v255, 23
	v_readlane_b32 s9, v255, 24
	v_add_u32_e32 v64, s10, v252
	s_lshl_b32 s73, s84, 6
	v_lshl_add_u64 v[196:197], s[8:9], 1, v[192:193]
	v_readlane_b32 s8, v255, 25
	v_readlane_b32 s9, v255, 26
	s_lshl_b32 s77, s3, 15
	v_subrev_u32_e32 v213, s73, v64
	v_lshl_add_u64 v[198:199], s[8:9], 1, v[192:193]
	v_readlane_b32 s8, v255, 27
	v_readlane_b32 s9, v255, 28
	s_mov_b64 s[88:89], 0
	v_mov_b32_e32 v191, 0
	v_lshl_add_u64 v[200:201], s[8:9], 1, v[192:193]
	v_mov_b32_e32 v181, 0
	v_mov_b32_e32 v180, 0
	v_mov_b32_e32 v145, v144
	v_mov_b32_e32 v146, v144
	v_mov_b32_e32 v147, v144
	v_mov_b32_e32 v148, v144
	v_mov_b32_e32 v149, v144
	v_mov_b32_e32 v150, v144
	v_mov_b32_e32 v151, v144
	v_mov_b32_e32 v152, v144
	v_mov_b32_e32 v153, v144
	v_mov_b32_e32 v154, v144
	v_mov_b32_e32 v155, v144
	v_mov_b32_e32 v156, v144
	v_mov_b32_e32 v157, v144
	v_mov_b32_e32 v158, v144
	v_mov_b32_e32 v159, v144
	s_cmp_eq_u32 s101, 1
	s_mov_b32 s101, 0
	s_cbranch_scc1 .Lc_pre_deep
	s_waitcnt vmcnt(0)
	s_branch .Lc_pre_join

; __device__ __forceinline__ void c_phase(const bf16_t* Z, bf16_t* MIX, float* LSE, ldsp lds, int pi, int bx, int G, unsigned& gt, int wave0, int ucount) {
;     ...
;         for (int kt = kt0; kt <= kt1; ++kt) {
;             const ldsp buf = lds + (gt & 1u) * 32768, nxt = lds + ((gt + 1u) & 1u) * 32768;
;             if (kt == kt1 - 1) {
;                 if (pi > 0) { lse_old = *lsep;
; #pragma unroll
;                     for (int i = 0; i < 4; ++i) orun[i] = ldg16(orow + i * ostep); }
.Lc_pre_join:
.LBB0_1036:
	s_cmp_eq_u32 s87, s84
	s_cselect_b64 s[90:91], -1, 0
	s_and_b64 s[8:9], s[82:83], s[90:91]
	s_andn2_b64 vcc, exec, s[8:9]
	s_cbranch_vccnz .LBB0_1038
	global_load_dword v191, v[194:195], off
	global_load_dwordx4 v[156:159], v[192:193], off
	global_load_dwordx4 v[152:155], v[196:197], off
	global_load_dwordx4 v[148:151], v[198:199], off
	global_load_dwordx4 v[144:147], v[200:201], off
